# NA loop specialised per wave half (queries in columns 0-31 or 32-63): the 12 score registers that are outside every lane's column window in that half get no LUT read, no bias add, no subtract and no e
# speedup vs baseline: 1.0063x; 1.0006x over previous
; #define ATT_MAX3(dst) do { float tm_ = max3f(sB0[0], sB1[0], sB0[1]), tn_ = max3f(sB1[1], sB0[2], sB1[2]); \
;         _Pragma("unroll") for (int r = 3; r < 15; r += 2) { tm_ = max3f(tm_, sB0[r], sB1[r]); tn_ = max3f(tn_, sB0[r + 1], sB1[r + 1]); } \
;         tm_ = max3f(tm_, sB0[15], sB1[15]); dst = max3f(tm_, tn_, tn_); } while (0)
; template <int MODE, bool FROZEN = false>
; __device__ __forceinline__ bool attn_unit(LAS unsigned char* lds, const Params& p, int l, int ua, int ub) {
;     ...
;     float cb_pos = 0.f, cb_neg = 0.f;
;     if constexpr (MODE == 1) { cb_pos = lut[448]; cb_neg = lut[0]; }
;     ATT_QK(0);
;     if constexpr (FROZEN) m_run = cb_neg;
;     { float tm0 = 0.f; if constexpr (!FROZEN) ATT_MAX3(tm0); ATT_BIAS(0, tm0); ATT_UPD(tm0); }
;     __syncthreads();
;     for (int t = 0; t < NT; ++t) {
.LBB0_257:
	v_add_f32_e32 v0, 0, v0
	v_max_f32_e32 v32, 0xf149f2ca, v0
	v_sub_f32_e32 v0, 0xf149f2ca, v32
	v_exp_f32_e32 v0, v0
	s_andn2_b64 vcc, exec, s[4:5]
	v_mul_f32_e32 v0, 0, v0
	v_cndmask_b32_e64 v0, v0, 0, s[0:1]
	v_mov_b32_e32 v1, v0
	v_mov_b32_e32 v2, v0
	v_mov_b32_e32 v3, v0
	v_mov_b32_e32 v4, v0
	v_mov_b32_e32 v5, v0
	v_mov_b32_e32 v6, v0
	v_mov_b32_e32 v7, v0
	v_mov_b32_e32 v8, v0
	v_mov_b32_e32 v9, v0
	v_mov_b32_e32 v10, v0
	v_mov_b32_e32 v11, v0
	v_mov_b32_e32 v12, v0
	v_mov_b32_e32 v13, v0
	v_mov_b32_e32 v14, v0
	v_mov_b32_e32 v15, v0
	v_mov_b32_e32 v16, v0
	v_mov_b32_e32 v17, v0
	v_mov_b32_e32 v18, v0
	v_mov_b32_e32 v19, v0
	v_mov_b32_e32 v20, v0
	v_mov_b32_e32 v21, v0
	v_mov_b32_e32 v22, v0
	v_mov_b32_e32 v23, v0
	v_mov_b32_e32 v24, v0
	v_mov_b32_e32 v25, v0
	v_mov_b32_e32 v26, v0
	v_mov_b32_e32 v27, v0
	v_mov_b32_e32 v28, v0
	v_mov_b32_e32 v29, v0
	v_mov_b32_e32 v30, v0
	v_mov_b32_e32 v31, v0
	s_cbranch_vccnz .LBB0_336
	v_add3_u32 v150, 0, v33, v196
	v_mov_b32_e32 v33, 0xf149f2ca
	v_cndmask_b32_e64 v152, v32, v33, s[0:1]
	v_min_u32_e32 v32, 48, v69
	v_sub_u32_e32 v32, v130, v32
	v_add_u32_e32 v35, 1, v32
	v_cmp_gt_u32_e64 s[42:43], 16, v35
	v_and_b32_e32 v35, -16, v35
	v_lshlrev_b32_e32 v33, 2, v68
	v_cmp_eq_u32_e64 s[44:45], s89, v35
	v_add_u32_e32 v35, 2, v32
	v_add3_u32 v151, 0, v196, v33
	v_and_b32_e32 v33, -16, v32
	v_cmp_gt_u32_e64 s[46:47], 16, v35
	v_and_b32_e32 v35, -16, v35
	v_cmp_eq_u32_e64 s[40:41], s89, v33
	v_cmp_eq_u32_e64 s[48:49], s89, v35
	v_add_u32_e32 v35, 3, v32
	v_cmp_eq_u32_e64 s[72:73], s88, v33
	v_add_u32_e32 v33, 17, v32
	v_cmp_gt_u32_e64 s[50:51], 16, v35
	v_and_b32_e32 v35, -16, v35
	s_movk_i32 s4, 0xffe0
	v_cmp_gt_u32_e64 s[74:75], 16, v33
	v_and_b32_e32 v33, -16, v33
	v_cmp_eq_u32_e64 s[52:53], s89, v35
	v_add_u32_e32 v35, 8, v32
	v_cmp_eq_u32_e64 s[76:77], s4, v33
	v_add_u32_e32 v33, 18, v32
	v_cmp_gt_u32_e64 s[54:55], 16, v35
	v_and_b32_e32 v35, -16, v35
	v_cmp_gt_u32_e64 s[78:79], 16, v33
	v_and_b32_e32 v33, -16, v33
	v_cmp_eq_u32_e64 s[56:57], s89, v35
	v_add_u32_e32 v35, 9, v32
	v_cmp_eq_u32_e64 s[80:81], s4, v33
	v_add_u32_e32 v33, 19, v32
	v_cmp_gt_u32_e64 s[58:59], 16, v35
	v_and_b32_e32 v35, -16, v35
	v_cmp_gt_u32_e64 s[82:83], 16, v33
	v_and_b32_e32 v33, -16, v33
	v_cmp_eq_u32_e64 s[60:61], s89, v35
	v_add_u32_e32 v35, 10, v32
	v_cmp_eq_u32_e64 s[84:85], s4, v33
	v_add_u32_e32 v33, 24, v32
	v_cmp_gt_u32_e64 s[62:63], 16, v35
	v_and_b32_e32 v35, -16, v35
	v_cmp_gt_u32_e64 s[86:87], 16, v33
	v_and_b32_e32 v33, -16, v33
	v_cmp_eq_u32_e64 s[64:65], s89, v35
	v_cmp_eq_u32_e64 s[88:89], s4, v33
	v_add_u32_e32 v33, 25, v32
	s_movk_i32 s0, 0xffef
	v_cmp_gt_u32_e64 s[90:91], 16, v33
	v_and_b32_e32 v33, -16, v33
	v_cmp_gt_u32_e64 s[38:39], 16, v32
	v_add_u32_e32 v35, 11, v32
	v_cmp_lt_u32_e64 s[70:71], s0, v32
	v_cmp_eq_u32_e64 s[92:93], s4, v33
	v_add_u32_e32 v33, 26, v32
	v_add_u32_e32 v32, 27, v32
	v_cmp_gt_u32_e64 s[66:67], 16, v35
	v_and_b32_e32 v35, -16, v35
	v_cmp_gt_u32_e64 s[94:95], 16, v33
	v_and_b32_e32 v33, -16, v33
	v_cmp_gt_u32_e64 s[0:1], 16, v32
	v_and_b32_e32 v32, -16, v32
	s_sub_i32 s11, s12, s11
	v_cmp_eq_u32_e64 s[68:69], s4, v35
	v_cmp_eq_u32_e64 s[96:97], s4, v33
	v_cmp_eq_u32_e64 s[4:5], s4, v32
	s_sub_i32 s19, s11, s10
	v_mov_b64_e32 v[32:33], v[30:31]
	s_add_i32 s17, s18, 12
	s_add_i32 s18, s18, 11
	s_add_i32 s19, s19, -3
	s_mov_b32 s21, 0
	v_mov_b64_e32 v[30:31], v[28:29]
	v_mov_b64_e32 v[28:29], v[26:27]
	v_mov_b64_e32 v[26:27], v[24:25]
	v_mov_b64_e32 v[24:25], v[22:23]
	v_mov_b64_e32 v[22:23], v[20:21]
	v_mov_b64_e32 v[20:21], v[18:19]
	v_mov_b64_e32 v[18:19], v[16:17]
	v_mov_b64_e32 v[16:17], v[14:15]
	v_mov_b64_e32 v[14:15], v[12:13]
	v_mov_b64_e32 v[12:13], v[10:11]
	v_mov_b64_e32 v[10:11], v[8:9]
	v_mov_b64_e32 v[8:9], v[6:7]
	v_mov_b64_e32 v[6:7], v[4:5]
	v_mov_b64_e32 v[4:5], v[2:3]
	v_mov_b64_e32 v[2:3], v[0:1]
	v_mov_b32_e32 v174, 0xf149f2ca
	s_nop 0
	v_cndmask_b32_e64 v202, v174, 0, s[38:39]
	v_cndmask_b32_e64 v176, v174, 0, s[40:41]
	v_cndmask_b32_e64 v203, v174, 0, s[42:43]
	v_cndmask_b32_e64 v177, v174, 0, s[44:45]
	v_cndmask_b32_e64 v204, v174, 0, s[46:47]
	v_cndmask_b32_e64 v178, v174, 0, s[48:49]
	v_cndmask_b32_e64 v205, v174, 0, s[50:51]
	v_cndmask_b32_e64 v179, v174, 0, s[52:53]
	v_cndmask_b32_e64 v206, v174, 0, s[54:55]
	v_cndmask_b32_e64 v180, v174, 0, s[56:57]
	v_cndmask_b32_e64 v207, v174, 0, s[58:59]
	v_cndmask_b32_e64 v181, v174, 0, s[60:61]
	v_cndmask_b32_e64 v208, v174, 0, s[62:63]
	v_cndmask_b32_e64 v182, v174, 0, s[64:65]
	v_cndmask_b32_e64 v209, v174, 0, s[66:67]
	v_cndmask_b32_e64 v183, v174, 0, s[68:69]
	v_cndmask_b32_e64 v210, v174, 0, s[70:71]
	v_cndmask_b32_e64 v184, v174, 0, s[72:73]
	v_cndmask_b32_e64 v211, v174, 0, s[74:75]
	v_cndmask_b32_e64 v185, v174, 0, s[76:77]
	v_cndmask_b32_e64 v212, v174, 0, s[78:79]
	v_cndmask_b32_e64 v186, v174, 0, s[80:81]
	v_cndmask_b32_e64 v213, v174, 0, s[82:83]
	v_cndmask_b32_e64 v187, v174, 0, s[84:85]
	v_cndmask_b32_e64 v214, v174, 0, s[86:87]
	v_cndmask_b32_e64 v188, v174, 0, s[88:89]
	v_cndmask_b32_e64 v215, v174, 0, s[90:91]
	v_cndmask_b32_e64 v189, v174, 0, s[92:93]
	v_cndmask_b32_e64 v216, v174, 0, s[94:95]
	v_cndmask_b32_e64 v190, v174, 0, s[96:97]
	v_cndmask_b32_e64 v217, v174, 0, s[0:1]
	v_cndmask_b32_e64 v191, v174, 0, s[4:5]
	v_readfirstlane_b32 s100, v228
	s_bitcmp1_b32 s100, 6
	s_cbranch_scc1 .Lna_entry_h1
	s_add_i32 s23, s21, 2
	s_cmp_ge_i32 s23, s17
	s_cbranch_scc1 .LBB0_260

; #define LAS __attribute__((address_space(3)))
; #define SBAR_() __builtin_amdgcn_sched_barrier(0)
; template <int MODE, bool FROZEN = false>
; __device__ __forceinline__ bool attn_unit(LAS unsigned char* lds, const Params& p, int l, int ua, int ub) {
;     ...
;         f32x16 sA0 = sB0, sA1 = sB1;
;         const float c2 = cbB - m_run;
;         const LAS unsigned char* Vb = lds + OFF_V + (t & 1) * VBUF + vlane_off;
;         const LAS unsigned char* Kb = lds + OFF_K + ((t + 1) & 1) * KBUF + klane_off;
;     ...
;         bf16x8 kf0[4], kf1[4], va[NB], vb[NB], pf0, pf1; float ps0, ps1, ps2, ps3;
;         VLOAD(0, va);
;         EXPCVT(0, pf0, ps0);
;         SBAR_();
;         VLOAD(1, vb); PVMMA(va, pf0); EXPCVT(1, pf1, ps1); _Pragma("unroll") for (int g_ = 0; g_ < NB; ++g_) { __builtin_amdgcn_sched_group_barrier(0x008, 1, 0); __builtin_amdgcn_sched_group_barrier(0x100, 1, 0); __builtin_amdgcn_sched_group_barrier(0x400, 8 / NB, 0); __builtin_amdgcn_sched_group_barrier(0x002, 12 / NB, 0); } SBAR_();
;         VLOAD(2, va);
; #pragma unroll
;         for (int d0 = 0; d0 < 4; ++d0) { kf0[d0] = *(const LAS bf16x8*)(Kb + d0 * 32); kf1[d0] = *(const LAS bf16x8*)(Kb + 32 * KPB + d0 * 32); }
;         PVMMA(vb, pf1); EXPCVT(2, pf0, ps2); _Pragma("unroll") for (int g_ = 0; g_ < NB; ++g_) { __builtin_amdgcn_sched_group_barrier(0x008, 1, 0); __builtin_amdgcn_sched_group_barrier(0x100, 1, 0); __builtin_amdgcn_sched_group_barrier(0x400, 8 / NB, 0); __builtin_amdgcn_sched_group_barrier(0x002, 12 / NB, 0); } SBAR_();
;         {
;             f32x16 z0, z1;
; #pragma unroll
;             for (int r = 0; r < 16; ++r) { z0[r] = 0.f; z1[r] = 0.f; }
; #pragma unroll
;             for (int d0 = 0; d0 < 4; ++d0) { z0 = __builtin_amdgcn_mfma_f32_32x32x16_bf16(kf0[d0], qf[d0], z0, 0, 0, 0); z1 = __builtin_amdgcn_mfma_f32_32x32x16_bf16(kf1[d0], qf[d0], z1, 0, 0, 0); }
;             sB0 = z0; sB1 = z1;
;         }
;         EXPCVT(3, pf1, ps3);
; #pragma unroll
;         for (int g_ = 0; g_ < 8; ++g_) { __builtin_amdgcn_sched_group_barrier(0x008, 1, 0); __builtin_amdgcn_sched_group_barrier(0x400, 1, 0); __builtin_amdgcn_sched_group_barrier(0x002, 2, 0); }
;         SBAR_();
;         float tmr;
;         VLOAD(3, vb); SBAR_();
;         PVMMA(va, pf0); if constexpr (!FROZEN) ATT_MAX3(tmr); else tmr = 0.f; PVMMA(vb, pf1);
;         const float ps = (ps0 + ps1) + (ps2 + ps3);
.LBB0_264:
	s_add_i32 s12, s21, 3
	s_min_i32 vcc_lo, s12, s18
	s_min_i32 s12, s23, s18
	s_ashr_i32 s13, s12, 31
	s_lshl_b64 s[12:13], s[12:13], 7
	v_mad_i64_i32 v[68:69], vcc, vcc_lo, v243, v[126:127]
	v_lshl_add_u64 v[70:71], v[128:129], 0, s[12:13]
	global_load_dwordx4 v[120:123], v[68:69], off
	global_load_dwordx4 v[116:119], v[70:71], off
	s_add_i32 s100, s21, 1
	s_cmp_lt_i32 s100, s16
	s_cbranch_scc1 .LBB0_334
	s_cmp_gt_i32 s21, s8
	s_cbranch_scc1 .LBB0_334
	v_add_f32_e64 v35, -v152, v52
	v_exp_f32_e32 v84, v35
	v_add_f32_e64 v35, -v152, v53
	v_exp_f32_e32 v86, v35
	v_add_f32_e64 v35, -v152, v54
	v_exp_f32_e32 v138, v35
	v_add_f32_e64 v35, -v152, v55
	v_exp_f32_e32 v142, v35
	v_add_f32_e64 v35, -v152, v56
	v_exp_f32_e32 v134, v35
	v_add_f32_e64 v35, -v152, v57
	s_bitcmp1_b32 s21, 0
	v_exp_f32_e32 v140, v35
	v_add_f32_e64 v35, -v152, v58
	s_cselect_b32 s12, 0x2400, 0
	v_exp_f32_e32 v132, v35
	v_add_f32_e64 v35, -v152, v59
	v_add_u32_e32 v1, s12, v150
	v_exp_f32_e32 v136, v35
	ds_read_b128 v[68:71], v1 offset:18432
	ds_read_b128 v[72:75], v1 offset:23040
	v_cvt_pk_bf16_f32 v52, v84, v86
	v_cvt_pk_bf16_f32 v53, v138, v142
	v_cvt_pk_bf16_f32 v54, v134, v140
	v_cvt_pk_bf16_f32 v55, v132, v136
	s_waitcnt lgkmcnt(1)
	s_nop 0
	v_mfma_f32_32x32x16_bf16 v[2:17], v[68:71], v[52:55], v[2:17]
	ds_read_b128 v[56:59], v1 offset:18464
	v_add_f32_e64 v60, -v152, v60
	v_exp_f32_e32 v98, v60
	v_add_f32_e64 v61, -v152, v61
	v_exp_f32_e32 v96, v61
	v_add_f32_e64 v62, -v152, v62
	v_exp_f32_e32 v146, v62
	v_add_f32_e64 v35, -v152, v64
	v_exp_f32_e32 v90, v35
	v_add_f32_e64 v35, -v152, v65
	v_exp_f32_e32 v94, v35
	v_add_f32_e64 v35, -v152, v66
	v_exp_f32_e32 v88, v35
	v_add_f32_e64 v35, -v152, v67
	v_exp_f32_e32 v92, v35
	v_add_f32_e64 v35, -v152, v63
	v_exp_f32_e32 v144, v35
	v_cvt_pk_bf16_f32 v62, v90, v94
	v_cvt_pk_bf16_f32 v63, v88, v92
	v_cvt_pk_bf16_f32 v61, v146, v144
	s_waitcnt lgkmcnt(1)
	v_mfma_f32_32x32x16_bf16 v[18:33], v[72:75], v[52:55], v[18:33]
	ds_read_b128 v[52:55], v1 offset:23072
	v_cvt_pk_bf16_f32 v60, v98, v96
	v_add_u32_e32 v35, s22, v149
	s_waitcnt lgkmcnt(1)
	v_mfma_f32_32x32x16_bf16 v[2:17], v[56:59], v[60:63], v[2:17]
	ds_read_b128 v[72:75], v1 offset:18496
	v_add_f32_e64 v36, -v152, v36
	v_exp_f32_e32 v85, v36
	v_mov_b32_e32 v137, 0
	v_add_f32_e64 v37, -v152, v37
	v_exp_f32_e32 v87, v37
	v_mov_b32_e32 v133, 0
	v_add_f32_e64 v38, -v152, v38
	v_exp_f32_e32 v139, v38
	v_mov_b32_e32 v141, 0
	v_add_f32_e64 v39, -v152, v39
	v_exp_f32_e32 v143, v39
	v_mov_b32_e32 v135, 0
	v_cvt_pk_bf16_f32 v83, v133, v137
	ds_read_b128 v[36:39], v35 offset:4608
	ds_read_b128 v[56:59], v35 offset:4640
	v_cvt_pk_bf16_f32 v82, v135, v141
	s_waitcnt lgkmcnt(3)
	v_mfma_f32_32x32x16_bf16 v[18:33], v[52:55], v[60:63], v[18:33]
	ds_read_b128 v[52:55], v35
	ds_read_b128 v[60:63], v35 offset:4672
	ds_read_b128 v[64:67], v35 offset:4704
	ds_read_b128 v[68:71], v1 offset:23104
	ds_read_b128 v[154:157], v35 offset:32
	ds_read_b128 v[158:161], v35 offset:64
	ds_read_b128 v[162:165], v35 offset:96
	v_cvt_pk_bf16_f32 v80, v85, v87
	v_cvt_pk_bf16_f32 v81, v139, v143
	v_mov_b32_e32 v93, 0
	v_mov_b32_e32 v99, 0
	v_mov_b32_e32 v147, 0
	v_mov_b32_e32 v89, 0
	v_mov_b32_e32 v97, 0
	s_waitcnt lgkmcnt(8)
	v_mfma_f32_32x32x16_bf16 v[36:51], v[36:39], v[100:103], v[176:191]
	s_waitcnt lgkmcnt(7)
	v_mfma_f32_32x32x16_bf16 v[36:51], v[56:59], v[104:107], v[36:51]
	s_waitcnt lgkmcnt(5)
	v_mfma_f32_32x32x16_bf16 v[36:51], v[60:63], v[108:111], v[36:51]
	s_waitcnt lgkmcnt(4)
	v_mfma_f32_32x32x16_bf16 v[36:51], v[64:67], v[112:115], v[36:51]
	v_mfma_f32_32x32x16_bf16 v[52:67], v[52:55], v[100:103], v[202:217]
	s_waitcnt lgkmcnt(2)
	v_mfma_f32_32x32x16_bf16 v[52:67], v[154:157], v[104:107], v[52:67]
	s_waitcnt lgkmcnt(1)
	v_mfma_f32_32x32x16_bf16 v[52:67], v[158:161], v[108:111], v[52:67]
	v_mov_b32_e32 v145, 0
	v_cvt_pk_bf16_f32 v76, v99, v97
	v_cvt_pk_bf16_f32 v77, v147, v145
	v_mov_b32_e32 v91, 0
	v_mov_b32_e32 v95, 0
	s_waitcnt lgkmcnt(0)
	v_mfma_f32_32x32x16_bf16 v[52:67], v[162:165], v[112:115], v[52:67]
	v_cvt_pk_bf16_f32 v79, v89, v93
	v_cvt_pk_bf16_f32 v78, v91, v95
	ds_read_b128 v[154:157], v1 offset:18528
	ds_read_b128 v[158:161], v1 offset:23136
	v_mfma_f32_32x32x16_bf16 v[2:17], v[72:75], v[80:83], v[2:17]
	v_add_f32_e64 v72, v138, v142
	v_add_f32_e64 v73, v139, v143
	v_add_f32_e64 v74, v134, v140
	v_add_f32_e64 v75, v135, v141
	v_add_f32_e64 v132, v132, v136
	v_add_f32_e64 v133, v133, v137
	v_pk_add_f32 v[84:85], v[84:85], v[86:87]
	v_pk_add_f32 v[74:75], v[74:75], v[132:133]
	s_andn2_b64 vcc, exec, s[10:11]
	v_mfma_f32_32x32x16_bf16 v[18:33], v[68:71], v[80:83], v[18:33]
	v_add_f32_e64 v68, v84, v72
	v_add_f32_e64 v69, v85, v73
	v_add_f32_e64 v72, v90, v94
	v_add_f32_e64 v73, v91, v95
	v_add_f32_e64 v68, v68, v74
	v_add_f32_e64 v69, v69, v75
	v_pk_add_f32 v[74:75], v[88:89], v[92:93]
	v_pk_add_f32 v[70:71], v[146:147], v[144:145]
	v_pk_add_f32 v[72:73], v[72:73], v[74:75]
	v_pk_add_f32 v[74:75], v[98:99], v[96:97]
	s_waitcnt lgkmcnt(1)
	v_mfma_f32_32x32x16_bf16 v[2:17], v[154:157], v[76:79], v[2:17]
	v_add_f32_e64 v70, v74, v70
	v_add_f32_e64 v71, v75, v71
	v_add_f32_e64 v70, v70, v72
	v_add_f32_e64 v71, v71, v73
	v_add_f32_e64 v68, v68, v70
	v_add_f32_e64 v69, v69, v71
	v_add_f32_e32 v1, v68, v69
	s_waitcnt lgkmcnt(0)
	v_mfma_f32_32x32x16_bf16 v[18:33], v[158:161], v[76:79], v[18:33]
	v_add_f32_e32 v0, v0, v1
	s_cbranch_vccnz .LBB0_334
	s_cmp_lt_i32 s20, s16
	s_cselect_b64 s[10:11], -1, 0
	s_cmp_ge_i32 s21, s8
	s_cselect_b64 s[12:13], -1, 0
	s_or_b64 s[10:11], s[12:13], s[10:11]
	s_and_b64 vcc, exec, s[10:11]
	s_cbranch_vccnz .LBB0_331
	s_add_i32 s10, s19, s21
	s_max_i32 s10, s10, -7
	s_add_i32 s10, s10, 7
	s_min_u32 s10, s10, 14
	s_mulk_i32 s10, 0x1fc
	v_add_u32_e32 v1, s10, v151
	v_mov_b32_e32 v35, 0xf149f2ca
	ds_read_b32 v68, v1 offset:36864
	ds_read_b32 v69, v1 offset:36992
	ds_read_b32 v70, v1 offset:36868
	ds_read_b32 v71, v1 offset:36996
	ds_read_b32 v72, v1 offset:36872
	ds_read_b32 v73, v1 offset:37000
	ds_read_b32 v74, v1 offset:36876
	ds_read_b32 v75, v1 offset:37004
	ds_read_b32 v76, v1 offset:36896
	ds_read_b32 v78, v1 offset:36900
	ds_read_b32 v80, v1 offset:36904
	ds_read_b32 v82, v1 offset:36908
	ds_read_b32 v84, v1 offset:36928
	ds_read_b32 v86, v1 offset:36932
	ds_read_b32 v88, v1 offset:36936
	s_waitcnt lgkmcnt(14)
	v_add_f32_e32 v52, v52, v68
	ds_read_b32 v90, v1 offset:36940
	s_waitcnt lgkmcnt(14)
	v_add_f32_e32 v36, v36, v69
	ds_read_b32 v92, v1 offset:36960
	s_waitcnt lgkmcnt(14)
	v_add_f32_e32 v53, v53, v70
	ds_read_b32 v94, v1 offset:36964
	s_waitcnt lgkmcnt(14)
	v_add_f32_e32 v37, v37, v71
	ds_read_b32 v96, v1 offset:36968
	s_waitcnt lgkmcnt(14)
	v_add_f32_e32 v54, v54, v72
	ds_read_b32 v98, v1 offset:36972
	s_waitcnt lgkmcnt(14)
	v_add_f32_e32 v38, v38, v73
	s_waitcnt lgkmcnt(13)
	v_add_f32_e32 v55, v55, v74
	s_waitcnt lgkmcnt(12)
	v_add_f32_e32 v39, v39, v75
	s_waitcnt lgkmcnt(11)
	v_add_f32_e32 v56, v56, v76
	s_waitcnt lgkmcnt(10)
	v_add_f32_e32 v57, v57, v78
	s_waitcnt lgkmcnt(9)
	v_add_f32_e32 v58, v58, v80
	s_waitcnt lgkmcnt(8)
	v_add_f32_e32 v59, v59, v82
	s_waitcnt lgkmcnt(7)
	v_add_f32_e32 v60, v60, v84
	s_waitcnt lgkmcnt(6)
	v_add_f32_e32 v61, v61, v86
	s_waitcnt lgkmcnt(5)
	v_add_f32_e32 v62, v62, v88
	s_waitcnt lgkmcnt(4)
	v_add_f32_e32 v63, v63, v90
	s_waitcnt lgkmcnt(3)
	v_add_f32_e32 v64, v64, v92
	s_waitcnt lgkmcnt(2)
	v_add_f32_e32 v65, v65, v94
	s_waitcnt lgkmcnt(1)
	v_add_f32_e32 v66, v66, v96
	s_waitcnt lgkmcnt(0)
	v_add_f32_e32 v67, v67, v98
	s_branch .LBB0_332

; #define LAS __attribute__((address_space(3)))
; template <int MODE, bool FROZEN = false>
; __device__ __forceinline__ bool attn_unit(LAS unsigned char* lds, const Params& p, int l, int ua, int ub) {
;     ...
;     for (int t = 0; t < NT; ++t) {
;         if (t + 2 < NT) {
; #pragma unroll
;             for (int i = 0; i < NKC; ++i) *(LAS u32x4*)(lds + kdst[i] + (t & 1) * KBUF) = kr[i];
;         }
;         if (t + 1 < NT) {
.Lna_entry_h1:
	s_add_i32 s23, s21, 2
	s_cmp_ge_i32 s23, s17
	s_cbranch_scc1 .LBB0_260_h1

; #define LAS __attribute__((address_space(3)))
; #define SBAR_() __builtin_amdgcn_sched_barrier(0)
; template <int MODE, bool FROZEN = false>
; __device__ __forceinline__ bool attn_unit(LAS unsigned char* lds, const Params& p, int l, int ua, int ub) {
;     ...
;         {
;             const size_t advk = (size_t)min(t + 3, NT - 1) * 64 * NPROJ, advv = (size_t)min(t + 2, NT - 1) * 64;
; #pragma unroll
;             for (int i = 0; i < NKC; ++i) kr[i] = *(const u32x4*)(kvbase + advk + ksrc[i]);
; #pragma unroll
;             for (int i = 0; i < NVC; ++i) vr[i] = *(const u32x4*)(vtbase + advv + vsrc[i]);
;         }
;         f32x16 sA0 = sB0, sA1 = sB1;
;         const float c2 = cbB - m_run;
;         const LAS unsigned char* Vb = lds + OFF_V + (t & 1) * VBUF + vlane_off;
;         const LAS unsigned char* Kb = lds + OFF_K + ((t + 1) & 1) * KBUF + klane_off;
;     ...
;         bf16x8 kf0[4], kf1[4], va[NB], vb[NB], pf0, pf1; float ps0, ps1, ps2, ps3;
;         VLOAD(0, va);
;         EXPCVT(0, pf0, ps0);
;         SBAR_();
;         VLOAD(1, vb); PVMMA(va, pf0); EXPCVT(1, pf1, ps1); _Pragma("unroll") for (int g_ = 0; g_ < NB; ++g_) { __builtin_amdgcn_sched_group_barrier(0x008, 1, 0); __builtin_amdgcn_sched_group_barrier(0x100, 1, 0); __builtin_amdgcn_sched_group_barrier(0x400, 8 / NB, 0); __builtin_amdgcn_sched_group_barrier(0x002, 12 / NB, 0); } SBAR_();
;         VLOAD(2, va);
; #pragma unroll
;         for (int d0 = 0; d0 < 4; ++d0) { kf0[d0] = *(const LAS bf16x8*)(Kb + d0 * 32); kf1[d0] = *(const LAS bf16x8*)(Kb + 32 * KPB + d0 * 32); }
;         PVMMA(vb, pf1); EXPCVT(2, pf0, ps2); _Pragma("unroll") for (int g_ = 0; g_ < NB; ++g_) { __builtin_amdgcn_sched_group_barrier(0x008, 1, 0); __builtin_amdgcn_sched_group_barrier(0x100, 1, 0); __builtin_amdgcn_sched_group_barrier(0x400, 8 / NB, 0); __builtin_amdgcn_sched_group_barrier(0x002, 12 / NB, 0); } SBAR_();
;         {
;             f32x16 z0, z1;
; #pragma unroll
;             for (int r = 0; r < 16; ++r) { z0[r] = 0.f; z1[r] = 0.f; }
; #pragma unroll
;             for (int d0 = 0; d0 < 4; ++d0) { z0 = __builtin_amdgcn_mfma_f32_32x32x16_bf16(kf0[d0], qf[d0], z0, 0, 0, 0); z1 = __builtin_amdgcn_mfma_f32_32x32x16_bf16(kf1[d0], qf[d0], z1, 0, 0, 0); }
;             sB0 = z0; sB1 = z1;
;         }
;         EXPCVT(3, pf1, ps3);
; #pragma unroll
.LBB0_264_h1:
	s_add_i32 s12, s21, 3
	s_min_i32 vcc_lo, s12, s18
	s_min_i32 s12, s23, s18
	s_ashr_i32 s13, s12, 31
	s_lshl_b64 s[12:13], s[12:13], 7
	v_mad_i64_i32 v[68:69], vcc, vcc_lo, v243, v[126:127]
	v_lshl_add_u64 v[70:71], v[128:129], 0, s[12:13]
	global_load_dwordx4 v[120:123], v[68:69], off
	global_load_dwordx4 v[116:119], v[70:71], off
	s_add_i32 s100, s21, 1
	s_cmp_lt_i32 s100, s16
	s_cbranch_scc1 .LBB0_334_h1
	s_cmp_gt_i32 s21, s8
	s_cbranch_scc1 .LBB0_334_h1
	v_mov_b32_e32 v84, 0
	v_mov_b32_e32 v86, 0
	v_mov_b32_e32 v138, 0
	v_mov_b32_e32 v142, 0
	v_mov_b32_e32 v134, 0
	s_bitcmp1_b32 s21, 0
	v_mov_b32_e32 v140, 0
	s_cselect_b32 s12, 0x2400, 0
	v_mov_b32_e32 v132, 0
	v_add_u32_e32 v1, s12, v150
	v_mov_b32_e32 v136, 0
	ds_read_b128 v[68:71], v1 offset:18432
	ds_read_b128 v[72:75], v1 offset:23040
	v_cvt_pk_bf16_f32 v52, v84, v86
	v_cvt_pk_bf16_f32 v53, v138, v142
	v_cvt_pk_bf16_f32 v54, v134, v140
	v_cvt_pk_bf16_f32 v55, v132, v136
	s_waitcnt lgkmcnt(1)
	s_nop 0
	v_mfma_f32_32x32x16_bf16 v[2:17], v[68:71], v[52:55], v[2:17]
	ds_read_b128 v[56:59], v1 offset:18464
	v_mov_b32_e32 v98, 0
	v_mov_b32_e32 v96, 0
	v_mov_b32_e32 v146, 0
	v_add_f32_e64 v35, -v152, v64
	v_exp_f32_e32 v90, v35
	v_add_f32_e64 v35, -v152, v65
	v_exp_f32_e32 v94, v35
	v_add_f32_e64 v35, -v152, v66
	v_exp_f32_e32 v88, v35
	v_add_f32_e64 v35, -v152, v67
	v_exp_f32_e32 v92, v35
	v_mov_b32_e32 v144, 0
	v_cvt_pk_bf16_f32 v62, v90, v94
	v_cvt_pk_bf16_f32 v63, v88, v92
	v_cvt_pk_bf16_f32 v61, v146, v144
	s_waitcnt lgkmcnt(1)
	v_mfma_f32_32x32x16_bf16 v[18:33], v[72:75], v[52:55], v[18:33]
	ds_read_b128 v[52:55], v1 offset:23072
	v_cvt_pk_bf16_f32 v60, v98, v96
	v_add_u32_e32 v35, s22, v149
	s_waitcnt lgkmcnt(1)
	v_mfma_f32_32x32x16_bf16 v[2:17], v[56:59], v[60:63], v[2:17]
	ds_read_b128 v[72:75], v1 offset:18496
	v_add_f32_e64 v36, -v152, v36
	v_exp_f32_e32 v85, v36
	v_add_f32_e64 v36, -v152, v43
	v_exp_f32_e32 v137, v36
	v_add_f32_e64 v37, -v152, v37
	v_exp_f32_e32 v87, v37
	v_add_f32_e64 v37, -v152, v42
	v_exp_f32_e32 v133, v37
	v_add_f32_e64 v38, -v152, v38
	v_exp_f32_e32 v139, v38
	v_add_f32_e64 v38, -v152, v41
	v_exp_f32_e32 v141, v38
	v_add_f32_e64 v39, -v152, v39
	v_exp_f32_e32 v143, v39
	v_add_f32_e64 v39, -v152, v40
	v_exp_f32_e32 v135, v39
	v_cvt_pk_bf16_f32 v83, v133, v137
	ds_read_b128 v[36:39], v35 offset:4608
	ds_read_b128 v[56:59], v35 offset:4640
	v_cvt_pk_bf16_f32 v82, v135, v141
	s_waitcnt lgkmcnt(3)
	v_mfma_f32_32x32x16_bf16 v[18:33], v[52:55], v[60:63], v[18:33]
	ds_read_b128 v[52:55], v35
	ds_read_b128 v[60:63], v35 offset:4672
	ds_read_b128 v[64:67], v35 offset:4704
	ds_read_b128 v[68:71], v1 offset:23104
	ds_read_b128 v[154:157], v35 offset:32
	ds_read_b128 v[158:161], v35 offset:64
	ds_read_b128 v[162:165], v35 offset:96
	v_cvt_pk_bf16_f32 v80, v85, v87
	v_cvt_pk_bf16_f32 v81, v139, v143
	v_add_f32_e64 v35, -v152, v51
	v_exp_f32_e32 v93, v35
	v_add_f32_e64 v35, -v152, v44
	v_exp_f32_e32 v99, v35
	v_add_f32_e64 v35, -v152, v46
	v_exp_f32_e32 v147, v35
	v_add_f32_e64 v35, -v152, v50
	v_exp_f32_e32 v89, v35
	v_add_f32_e64 v40, -v152, v45
	v_add_f32_e64 v76, -v152, v47
	v_add_f32_e64 v78, -v152, v48
	v_exp_f32_e32 v97, v40
	v_add_f32_e64 v79, -v152, v49
	s_waitcnt lgkmcnt(8)
	v_mfma_f32_32x32x16_bf16 v[36:51], v[36:39], v[100:103], v[176:191]
	s_waitcnt lgkmcnt(7)
	v_mfma_f32_32x32x16_bf16 v[36:51], v[56:59], v[104:107], v[36:51]
	s_waitcnt lgkmcnt(5)
	v_mfma_f32_32x32x16_bf16 v[36:51], v[60:63], v[108:111], v[36:51]
	s_waitcnt lgkmcnt(4)
	v_mfma_f32_32x32x16_bf16 v[36:51], v[64:67], v[112:115], v[36:51]
	v_mfma_f32_32x32x16_bf16 v[52:67], v[52:55], v[100:103], v[202:217]
	s_waitcnt lgkmcnt(2)
	v_mfma_f32_32x32x16_bf16 v[52:67], v[154:157], v[104:107], v[52:67]
	s_waitcnt lgkmcnt(1)
	v_mfma_f32_32x32x16_bf16 v[52:67], v[158:161], v[108:111], v[52:67]
	v_exp_f32_e32 v145, v76
	v_cvt_pk_bf16_f32 v76, v99, v97
	v_cvt_pk_bf16_f32 v77, v147, v145
	v_exp_f32_e32 v91, v78
	v_exp_f32_e32 v95, v79
	s_waitcnt lgkmcnt(0)
	v_mfma_f32_32x32x16_bf16 v[52:67], v[162:165], v[112:115], v[52:67]
	v_cvt_pk_bf16_f32 v79, v89, v93
	v_cvt_pk_bf16_f32 v78, v91, v95
	ds_read_b128 v[154:157], v1 offset:18528
	ds_read_b128 v[158:161], v1 offset:23136
	v_mfma_f32_32x32x16_bf16 v[2:17], v[72:75], v[80:83], v[2:17]
	v_add_f32_e64 v72, v138, v142
	v_add_f32_e64 v73, v139, v143
	v_add_f32_e64 v74, v134, v140
	v_add_f32_e64 v75, v135, v141
	v_add_f32_e64 v132, v132, v136
	v_add_f32_e64 v133, v133, v137
	v_pk_add_f32 v[84:85], v[84:85], v[86:87]
	v_pk_add_f32 v[74:75], v[74:75], v[132:133]
	s_andn2_b64 vcc, exec, s[10:11]
	v_mfma_f32_32x32x16_bf16 v[18:33], v[68:71], v[80:83], v[18:33]
	v_add_f32_e64 v68, v84, v72
	v_add_f32_e64 v69, v85, v73
	v_add_f32_e64 v72, v90, v94
	v_add_f32_e64 v73, v91, v95
	v_add_f32_e64 v68, v68, v74
	v_add_f32_e64 v69, v69, v75
	v_pk_add_f32 v[74:75], v[88:89], v[92:93]
	v_pk_add_f32 v[70:71], v[146:147], v[144:145]
	v_pk_add_f32 v[72:73], v[72:73], v[74:75]
	v_pk_add_f32 v[74:75], v[98:99], v[96:97]
	s_waitcnt lgkmcnt(1)
	v_mfma_f32_32x32x16_bf16 v[2:17], v[154:157], v[76:79], v[2:17]
	v_add_f32_e64 v70, v74, v70
	v_add_f32_e64 v71, v75, v71
	v_add_f32_e64 v70, v70, v72
	v_add_f32_e64 v71, v71, v73
	v_add_f32_e64 v68, v68, v70
	v_add_f32_e64 v69, v69, v71
	v_add_f32_e32 v1, v68, v69
	s_waitcnt lgkmcnt(0)
	v_mfma_f32_32x32x16_bf16 v[18:33], v[158:161], v[76:79], v[18:33]
	v_add_f32_e32 v0, v0, v1
	s_cbranch_vccnz .LBB0_334_h1
	s_cmp_lt_i32 s20, s16
	s_cselect_b64 s[10:11], -1, 0
	s_cmp_ge_i32 s21, s8
	s_cselect_b64 s[12:13], -1, 0
	s_or_b64 s[10:11], s[12:13], s[10:11]
	s_and_b64 vcc, exec, s[10:11]
	s_cbranch_vccnz .LBB0_331_h1
	s_add_i32 s10, s19, s21
	s_max_i32 s10, s10, -7
	s_add_i32 s10, s10, 7
	s_min_u32 s10, s10, 14
	s_mulk_i32 s10, 0x1fc
	v_add_u32_e32 v1, s10, v151
	v_mov_b32_e32 v35, 0xf149f2ca
	ds_read_b32 v69, v1 offset:36992
	ds_read_b32 v71, v1 offset:36996
	ds_read_b32 v73, v1 offset:37000
	ds_read_b32 v75, v1 offset:37004
	ds_read_b32 v77, v1 offset:37024
	ds_read_b32 v79, v1 offset:37028
	ds_read_b32 v81, v1 offset:37032
	ds_read_b32 v83, v1 offset:37036
	ds_read_b32 v85, v1 offset:37056
	ds_read_b32 v87, v1 offset:37060
	ds_read_b32 v89, v1 offset:37064
	ds_read_b32 v91, v1 offset:37068
	ds_read_b32 v92, v1 offset:36960
	ds_read_b32 v93, v1 offset:37088
	ds_read_b32 v94, v1 offset:36964
	s_waitcnt lgkmcnt(14)
	v_add_f32_e32 v36, v36, v69
	ds_read_b32 v95, v1 offset:37092
	s_waitcnt lgkmcnt(14)
	v_add_f32_e32 v37, v37, v71
	ds_read_b32 v96, v1 offset:36968
	s_waitcnt lgkmcnt(14)
	v_add_f32_e32 v38, v38, v73
	ds_read_b32 v97, v1 offset:37096
	s_waitcnt lgkmcnt(14)
	v_add_f32_e32 v39, v39, v75
	ds_read_b32 v98, v1 offset:36972
	s_waitcnt lgkmcnt(14)
	v_add_f32_e32 v40, v40, v77
	ds_read_b32 v99, v1 offset:37100
	s_waitcnt lgkmcnt(14)
	v_add_f32_e32 v41, v41, v79
	s_waitcnt lgkmcnt(13)
	v_add_f32_e32 v42, v42, v81
	s_waitcnt lgkmcnt(12)
	v_add_f32_e32 v43, v43, v83
	s_waitcnt lgkmcnt(11)
	v_add_f32_e32 v44, v44, v85
	s_waitcnt lgkmcnt(10)
	v_add_f32_e32 v45, v45, v87
	s_waitcnt lgkmcnt(9)
	v_add_f32_e32 v46, v46, v89
	s_waitcnt lgkmcnt(8)
	v_add_f32_e32 v47, v47, v91
	s_waitcnt lgkmcnt(7)
	v_add_f32_e32 v64, v64, v92
	s_waitcnt lgkmcnt(6)
	v_add_f32_e32 v48, v48, v93
	s_waitcnt lgkmcnt(5)
	v_add_f32_e32 v65, v65, v94
	s_waitcnt lgkmcnt(4)
	v_add_f32_e32 v49, v49, v95
	s_waitcnt lgkmcnt(3)
	v_add_f32_e32 v66, v66, v96
	s_waitcnt lgkmcnt(2)
	v_add_f32_e32 v50, v50, v97
	s_waitcnt lgkmcnt(1)
	v_add_f32_e32 v67, v67, v98
	s_waitcnt lgkmcnt(0)
	v_add_f32_e32 v51, v51, v99
	s_branch .LBB0_332_h1
